# W_in K-loop: removed the full lgkmcnt(0) wait in the middle of interval-1's ds_read burst (no dependency on it)
# speedup vs baseline: 1.0064x; 1.0064x over previous
; #define PG8_STAGE(bufoff, gbase, voff) do { _Pragma("unroll") for (int _i = 0; _i < 2; ++_i) \
;         __builtin_amdgcn_global_load_lds((const unsigned*)((const char*)(gbase) + (voff)[_i]), (PG8_LAS unsigned*)(lds + (bufoff) + ldsw + _i * 8192), 16, 0, 0); } while (0)
; #define PG8_LDA(dst, b, h) do { _Pragma("unroll") for (int m = 0; m < 4; ++m) _Pragma("unroll") for (int k = 0; k < 2; ++k) dst[m][k] = *(const PG8_LAS bf16x8*)(lds + PG8_SA(b, h) + aoff + m * 2048 + k * 1024); } while (0)
; #define PG8_LDB(dst, b, h) do { _Pragma("unroll") for (int n = 0; n < 2; ++n) _Pragma("unroll") for (int k = 0; k < 2; ++k) dst[n][k] = *(const PG8_LAS bf16x8*)(lds + PG8_SB(b, h) + boff + n * 2048 + k * 1024); } while (0)
; #define PG8_MMA(ai, bj, At, Bt) do { __builtin_amdgcn_s_setprio(1); _Pragma("unroll") for (int m = 0; m < 4; ++m) _Pragma("unroll") for (int n = 0; n < 2; ++n) _Pragma("unroll") for (int k = 0; k < 2; ++k) \
;         acc[ai][bj][m][n] = __builtin_amdgcn_mfma_f32_16x16x32_bf16(Bt[n][k], At[m][k], acc[ai][bj][m][n], 0, 0, 0); __builtin_amdgcn_s_setprio(0); } while (0)
; #define PG8_WAIT_V(n) asm volatile("s_waitcnt vmcnt(" #n ")" ::: "memory")
; #define PG8_WAIT_L(n) asm volatile("s_waitcnt lgkmcnt(" #n ")" ::: "memory")
; #define PG8_BAR __builtin_amdgcn_s_barrier()
; #define PG8_SCHED __builtin_amdgcn_sched_barrier(0)
; template <class Epi, class Sched, bool ALIGN_EPI = false, bool SP2 = false>
; __device__ __forceinline__ void gemm_phase(PG8_LAS unsigned char* lds, const Gemm g, const Sched& S, const Epi& E, int wave0) {
;     ...
;             PG8_LDB(B0, 0, 0); PG8_LDB(B1, 0, 1); PG8_SCHED; PG8_LDA(At, 0, 0); PG8_STAGE(PG8_SA(1, 1), a1 + hstep, voffA);
;             PG8_WAIT_V(8); PG8_WAIT_L(0); PG8_BAR; PG8_MMA(0, 0, At, B0); PG8_MMA(0, 1, At, B1); PG8_BAR; PG8_SCHED;
;             PG8_LDA(At, 0, 1); PG8_STAGE(PG8_SB(0, 0), b2, voffB); PG8_STAGE(PG8_SB(0, 1), b2 + hstep, voffB); PG8_STAGE(PG8_SA(0, 0), a2, voffA);
;             PG8_WAIT_V(8); PG8_WAIT_L(0); PG8_BAR; PG8_MMA(1, 0, At, B0); PG8_MMA(1, 1, At, B1); PG8_BAR; PG8_SCHED;
.LBB0_195:
	s_add_u32 s4, s0, 0xfffc0080
	s_addc_u32 s5, s1, -1
	s_add_i32 s86, 0, 0x10000
	s_cmp_eq_u32 s85, 12
	s_cselect_b32 s43, s44, s5
	s_cselect_b32 s42, s53, s4
	v_add_u32_e32 v0, s86, v174
	s_cselect_b32 s5, s51, s84
	s_cselect_b32 s4, s82, s83
	s_add_i32 s88, 0, 0x14000
	ds_read_b128 v[130:133], v0
	ds_read_b128 v[134:137], v0 offset:1024
	ds_read_b128 v[138:141], v0 offset:2048
	ds_read_b128 v[142:145], v0 offset:3072
	v_add_u32_e32 v0, s88, v174
	ds_read_b128 v[158:161], v0
	ds_read_b128 v[162:165], v0 offset:1024
	ds_read_b128 v[166:169], v0 offset:2048
	ds_read_b128 v[170:173], v0 offset:3072
	v_lshl_add_u64 v[208:209], s[0:1], 0, v[154:155]
	s_add_i32 m0, s62, 0xc000
	ds_read_b128 v[176:179], v175
	ds_read_b128 v[180:183], v175 offset:1024
	ds_read_b128 v[184:187], v175 offset:2048
	ds_read_b128 v[188:191], v175 offset:3072
	ds_read_b128 v[192:195], v175 offset:4096
	ds_read_b128 v[196:199], v175 offset:5120
	ds_read_b128 v[200:203], v175 offset:6144
	ds_read_b128 v[204:207], v175 offset:7168
	global_load_lds_dwordx4 v[208:209], off
	v_lshl_add_u64 v[208:209], s[0:1], 0, v[156:157]
	s_add_i32 m0, s62, 0xe000
	s_nop 0
	global_load_lds_dwordx4 v[208:209], off
	s_waitcnt vmcnt(8)
	s_waitcnt lgkmcnt(0)
	s_barrier
	s_setprio 1
	s_waitcnt lgkmcnt(0)
	v_mfma_f32_16x16x32_bf16 v[126:129], v[130:133], v[176:179], v[126:129]
	v_mfma_f32_16x16x32_bf16 v[122:125], v[138:141], v[176:179], v[122:125]
	v_mfma_f32_16x16x32_bf16 v[110:113], v[130:133], v[184:187], v[110:113]
	v_mfma_f32_16x16x32_bf16 v[106:109], v[138:141], v[184:187], v[106:109]
	v_mfma_f32_16x16x32_bf16 v[94:97], v[130:133], v[192:195], v[94:97]
	v_mfma_f32_16x16x32_bf16 v[90:93], v[138:141], v[192:195], v[90:93]
	v_mfma_f32_16x16x32_bf16 v[78:81], v[130:133], v[200:203], v[78:81]
	v_mfma_f32_16x16x32_bf16 v[74:77], v[138:141], v[200:203], v[74:77]
	v_mfma_f32_16x16x32_bf16 v[126:129], v[134:137], v[180:183], v[126:129]
	v_mfma_f32_16x16x32_bf16 v[122:125], v[142:145], v[180:183], v[122:125]
	v_mfma_f32_16x16x32_bf16 v[110:113], v[134:137], v[188:191], v[110:113]
	v_mfma_f32_16x16x32_bf16 v[106:109], v[142:145], v[188:191], v[106:109]
	v_mfma_f32_16x16x32_bf16 v[94:97], v[134:137], v[196:199], v[94:97]
	v_mfma_f32_16x16x32_bf16 v[90:93], v[142:145], v[196:199], v[90:93]
	v_mfma_f32_16x16x32_bf16 v[78:81], v[134:137], v[204:207], v[78:81]
	v_mfma_f32_16x16x32_bf16 v[74:77], v[142:145], v[204:207], v[74:77]
	s_setprio 0
	s_setprio 1
	v_mfma_f32_16x16x32_bf16 v[118:121], v[158:161], v[176:179], v[118:121]
	v_mfma_f32_16x16x32_bf16 v[114:117], v[166:169], v[176:179], v[114:117]
	v_mfma_f32_16x16x32_bf16 v[102:105], v[158:161], v[184:187], v[102:105]
	v_mfma_f32_16x16x32_bf16 v[98:101], v[166:169], v[184:187], v[98:101]
	v_mfma_f32_16x16x32_bf16 v[86:89], v[158:161], v[192:195], v[86:89]
	v_mfma_f32_16x16x32_bf16 v[82:85], v[166:169], v[192:195], v[82:85]
	v_mfma_f32_16x16x32_bf16 v[70:73], v[158:161], v[200:203], v[70:73]
	v_mfma_f32_16x16x32_bf16 v[66:69], v[166:169], v[200:203], v[66:69]
	v_mfma_f32_16x16x32_bf16 v[118:121], v[162:165], v[180:183], v[118:121]
	v_mfma_f32_16x16x32_bf16 v[114:117], v[170:173], v[180:183], v[114:117]
	v_mfma_f32_16x16x32_bf16 v[102:105], v[162:165], v[188:191], v[102:105]
	v_mfma_f32_16x16x32_bf16 v[98:101], v[170:173], v[188:191], v[98:101]
	v_mfma_f32_16x16x32_bf16 v[86:89], v[162:165], v[196:199], v[86:89]
	v_mfma_f32_16x16x32_bf16 v[82:85], v[170:173], v[196:199], v[82:85]
	v_mfma_f32_16x16x32_bf16 v[70:73], v[162:165], v[204:207], v[70:73]
	v_mfma_f32_16x16x32_bf16 v[66:69], v[170:173], v[204:207], v[66:69]
	s_setprio 0
	s_barrier
	s_add_i32 s86, s86, s61
	v_lshl_add_u64 v[208:209], s[4:5], 0, v[150:151]
	s_mov_b32 m0, s86
	ds_read_b128 v[176:179], v175 offset:16384
	ds_read_b128 v[180:183], v175 offset:17408
	ds_read_b128 v[184:187], v175 offset:18432
	ds_read_b128 v[188:191], v175 offset:19456
	ds_read_b128 v[192:195], v175 offset:20480
	ds_read_b128 v[196:199], v175 offset:21504
	ds_read_b128 v[200:203], v175 offset:22528
	ds_read_b128 v[204:207], v175 offset:23552
	global_load_lds_dwordx4 v[208:209], off
	s_add_i32 m0, s86, 0x2000
	s_add_u32 s86, s4, 0x40000
	v_lshl_add_u64 v[210:211], s[4:5], 0, v[146:147]
	s_addc_u32 s87, s5, 0
	s_add_i32 s88, s88, s61
	global_load_lds_dwordx4 v[210:211], off
	v_lshl_add_u64 v[212:213], s[86:87], 0, v[150:151]
	s_mov_b32 m0, s88
	v_lshl_add_u64 v[214:215], s[42:43], 0, v[148:149]
	global_load_lds_dwordx4 v[212:213], off
	v_lshl_add_u64 v[212:213], s[86:87], 0, v[146:147]
	s_add_i32 m0, s88, 0x2000
	s_nop 0
	global_load_lds_dwordx4 v[212:213], off
	v_lshl_add_u64 v[212:213], s[42:43], 0, v[152:153]
	s_mov_b32 m0, s62
	s_nop 0
	global_load_lds_dwordx4 v[212:213], off
	s_mov_b32 m0, s63
	s_nop 0
	global_load_lds_dwordx4 v[214:215], off
	s_waitcnt vmcnt(8)
	s_waitcnt lgkmcnt(0)
	s_barrier
; #define PG8_STAGE(bufoff, gbase, voff) do { _Pragma("unroll") for (int _i = 0; _i < 2; ++_i) \
;         __builtin_amdgcn_global_load_lds((const unsigned*)((const char*)(gbase) + (voff)[_i]), (PG8_LAS unsigned*)(lds + (bufoff) + ldsw + _i * 8192), 16, 0, 0); } while (0)
; #define PG8_LDA(dst, b, h) do { _Pragma("unroll") for (int m = 0; m < 4; ++m) _Pragma("unroll") for (int k = 0; k < 2; ++k) dst[m][k] = *(const PG8_LAS bf16x8*)(lds + PG8_SA(b, h) + aoff + m * 2048 + k * 1024); } while (0)
; #define PG8_LDB(dst, b, h) do { _Pragma("unroll") for (int n = 0; n < 2; ++n) _Pragma("unroll") for (int k = 0; k < 2; ++k) dst[n][k] = *(const PG8_LAS bf16x8*)(lds + PG8_SB(b, h) + boff + n * 2048 + k * 1024); } while (0)
; #define PG8_MMA(ai, bj, At, Bt) do { __builtin_amdgcn_s_setprio(1); _Pragma("unroll") for (int m = 0; m < 4; ++m) _Pragma("unroll") for (int n = 0; n < 2; ++n) _Pragma("unroll") for (int k = 0; k < 2; ++k) \
;         acc[ai][bj][m][n] = __builtin_amdgcn_mfma_f32_16x16x32_bf16(Bt[n][k], At[m][k], acc[ai][bj][m][n], 0, 0, 0); __builtin_amdgcn_s_setprio(0); } while (0)
; #define PG8_WAIT_V(n) asm volatile("s_waitcnt vmcnt(" #n ")" ::: "memory")
; #define PG8_WAIT_L(n) asm volatile("s_waitcnt lgkmcnt(" #n ")" ::: "memory")
; #define PG8_BAR __builtin_amdgcn_s_barrier()
; #define PG8_SCHED __builtin_amdgcn_sched_barrier(0)
; template <class Epi, class Sched, bool ALIGN_EPI = false, bool SP2 = false>
; __device__ __forceinline__ void gemm_phase(PG8_LAS unsigned char* lds, const Gemm g, const Sched& S, const Epi& E, int wave0) {
;     ...
;             PG8_WAIT_V(8); PG8_WAIT_L(0); PG8_BAR; PG8_MMA(1, 0, At, B0); PG8_MMA(1, 1, At, B1); PG8_BAR; PG8_SCHED;
;             PG8_LDB(B0, 1, 0); PG8_LDB(B1, 1, 1); PG8_SCHED; PG8_LDA(At, 1, 0); PG8_STAGE(PG8_SA(0, 1), a2 + hstep, voffA);
;             PG8_WAIT_V(8); PG8_WAIT_L(0); PG8_BAR; PG8_MMA(0, 0, At, B0); PG8_MMA(0, 1, At, B1); PG8_BAR; PG8_SCHED;
	s_setprio 1
	s_waitcnt lgkmcnt(0)
	v_mfma_f32_16x16x32_bf16 v[62:65], v[130:133], v[176:179], v[62:65]
	v_mfma_f32_16x16x32_bf16 v[58:61], v[138:141], v[176:179], v[58:61]
	v_mfma_f32_16x16x32_bf16 v[46:49], v[130:133], v[184:187], v[46:49]
	v_mfma_f32_16x16x32_bf16 v[42:45], v[138:141], v[184:187], v[42:45]
	v_mfma_f32_16x16x32_bf16 v[30:33], v[130:133], v[192:195], v[30:33]
	v_mfma_f32_16x16x32_bf16 v[26:29], v[138:141], v[192:195], v[26:29]
	v_mfma_f32_16x16x32_bf16 v[14:17], v[130:133], v[200:203], v[14:17]
	v_mfma_f32_16x16x32_bf16 v[10:13], v[138:141], v[200:203], v[10:13]
	v_mfma_f32_16x16x32_bf16 v[62:65], v[134:137], v[180:183], v[62:65]
	v_mfma_f32_16x16x32_bf16 v[58:61], v[142:145], v[180:183], v[58:61]
	v_mfma_f32_16x16x32_bf16 v[46:49], v[134:137], v[188:191], v[46:49]
	v_mfma_f32_16x16x32_bf16 v[42:45], v[142:145], v[188:191], v[42:45]
	v_mfma_f32_16x16x32_bf16 v[30:33], v[134:137], v[196:199], v[30:33]
	v_mfma_f32_16x16x32_bf16 v[26:29], v[142:145], v[196:199], v[26:29]
	v_mfma_f32_16x16x32_bf16 v[14:17], v[134:137], v[204:207], v[14:17]
	v_mfma_f32_16x16x32_bf16 v[10:13], v[142:145], v[204:207], v[10:13]
	s_setprio 0
	s_setprio 1
	v_mfma_f32_16x16x32_bf16 v[54:57], v[158:161], v[176:179], v[54:57]
	v_mfma_f32_16x16x32_bf16 v[50:53], v[166:169], v[176:179], v[50:53]
	v_mfma_f32_16x16x32_bf16 v[38:41], v[158:161], v[184:187], v[38:41]
	v_mfma_f32_16x16x32_bf16 v[34:37], v[166:169], v[184:187], v[34:37]
	v_mfma_f32_16x16x32_bf16 v[22:25], v[158:161], v[192:195], v[22:25]
	v_mfma_f32_16x16x32_bf16 v[18:21], v[166:169], v[192:195], v[18:21]
	v_mfma_f32_16x16x32_bf16 v[6:9], v[158:161], v[200:203], v[6:9]
	v_mfma_f32_16x16x32_bf16 v[2:5], v[166:169], v[200:203], v[2:5]
	v_mfma_f32_16x16x32_bf16 v[54:57], v[162:165], v[180:183], v[54:57]
	v_mfma_f32_16x16x32_bf16 v[50:53], v[170:173], v[180:183], v[50:53]
	v_mfma_f32_16x16x32_bf16 v[38:41], v[162:165], v[188:191], v[38:41]
	v_mfma_f32_16x16x32_bf16 v[34:37], v[170:173], v[188:191], v[34:37]
	v_mfma_f32_16x16x32_bf16 v[22:25], v[162:165], v[196:199], v[22:25]
	v_mfma_f32_16x16x32_bf16 v[18:21], v[170:173], v[196:199], v[18:21]
	v_mfma_f32_16x16x32_bf16 v[6:9], v[162:165], v[204:207], v[6:9]
	v_mfma_f32_16x16x32_bf16 v[2:5], v[170:173], v[204:207], v[2:5]
	s_setprio 0
	s_barrier
	s_add_i32 s86, 0, 0x18000
	v_add_u32_e32 v0, s86, v174
	s_add_i32 s87, 0, 0x1c000
	ds_read_b128 v[130:133], v0
	ds_read_b128 v[134:137], v0 offset:1024
	ds_read_b128 v[138:141], v0 offset:2048
	ds_read_b128 v[142:145], v0 offset:3072
	v_add_u32_e32 v0, s87, v174
	ds_read_b128 v[158:161], v0
	ds_read_b128 v[162:165], v0 offset:1024
	ds_read_b128 v[166:169], v0 offset:2048
	ds_read_b128 v[170:173], v0 offset:3072
	s_add_u32 s42, s42, 0x40000
	s_addc_u32 s43, s43, 0
	s_mov_b32 m0, s64
	v_lshl_add_u64 v[216:217], s[42:43], 0, v[152:153]
	ds_read_b128 v[176:179], v175 offset:32768
	ds_read_b128 v[180:183], v175 offset:33792
	ds_read_b128 v[184:187], v175 offset:34816
	ds_read_b128 v[188:191], v175 offset:35840
	ds_read_b128 v[192:195], v175 offset:36864
	ds_read_b128 v[196:199], v175 offset:37888
	ds_read_b128 v[200:203], v175 offset:38912
	ds_read_b128 v[204:207], v175 offset:39936
	global_load_lds_dwordx4 v[216:217], off
	v_lshl_add_u64 v[216:217], s[42:43], 0, v[148:149]
	s_mov_b32 m0, s65
	s_nop 0
	global_load_lds_dwordx4 v[216:217], off
	s_waitcnt vmcnt(8)
	s_waitcnt lgkmcnt(0)
	s_barrier
	s_setprio 1
	s_waitcnt lgkmcnt(0)
	v_mfma_f32_16x16x32_bf16 v[126:129], v[130:133], v[176:179], v[126:129]
	v_mfma_f32_16x16x32_bf16 v[122:125], v[138:141], v[176:179], v[122:125]
	v_mfma_f32_16x16x32_bf16 v[110:113], v[130:133], v[184:187], v[110:113]
	v_mfma_f32_16x16x32_bf16 v[106:109], v[138:141], v[184:187], v[106:109]
	v_mfma_f32_16x16x32_bf16 v[94:97], v[130:133], v[192:195], v[94:97]
	v_mfma_f32_16x16x32_bf16 v[90:93], v[138:141], v[192:195], v[90:93]
	v_mfma_f32_16x16x32_bf16 v[78:81], v[130:133], v[200:203], v[78:81]
	v_mfma_f32_16x16x32_bf16 v[74:77], v[138:141], v[200:203], v[74:77]
	v_mfma_f32_16x16x32_bf16 v[126:129], v[134:137], v[180:183], v[126:129]
	v_mfma_f32_16x16x32_bf16 v[122:125], v[142:145], v[180:183], v[122:125]
	v_mfma_f32_16x16x32_bf16 v[110:113], v[134:137], v[188:191], v[110:113]
	v_mfma_f32_16x16x32_bf16 v[106:109], v[142:145], v[188:191], v[106:109]
	v_mfma_f32_16x16x32_bf16 v[94:97], v[134:137], v[196:199], v[94:97]
	v_mfma_f32_16x16x32_bf16 v[90:93], v[142:145], v[196:199], v[90:93]
	v_mfma_f32_16x16x32_bf16 v[78:81], v[134:137], v[204:207], v[78:81]
	v_mfma_f32_16x16x32_bf16 v[74:77], v[142:145], v[204:207], v[74:77]
	s_setprio 0
	s_setprio 1
	v_mfma_f32_16x16x32_bf16 v[118:121], v[158:161], v[176:179], v[118:121]
	v_mfma_f32_16x16x32_bf16 v[114:117], v[166:169], v[176:179], v[114:117]
	v_mfma_f32_16x16x32_bf16 v[102:105], v[158:161], v[184:187], v[102:105]
	v_mfma_f32_16x16x32_bf16 v[98:101], v[166:169], v[184:187], v[98:101]
	v_mfma_f32_16x16x32_bf16 v[86:89], v[158:161], v[192:195], v[86:89]
	v_mfma_f32_16x16x32_bf16 v[82:85], v[166:169], v[192:195], v[82:85]
	v_mfma_f32_16x16x32_bf16 v[70:73], v[158:161], v[200:203], v[70:73]
	v_mfma_f32_16x16x32_bf16 v[66:69], v[166:169], v[200:203], v[66:69]
	v_mfma_f32_16x16x32_bf16 v[118:121], v[162:165], v[180:183], v[118:121]
	v_mfma_f32_16x16x32_bf16 v[114:117], v[170:173], v[180:183], v[114:117]
	v_mfma_f32_16x16x32_bf16 v[102:105], v[162:165], v[188:191], v[102:105]
	v_mfma_f32_16x16x32_bf16 v[98:101], v[170:173], v[188:191], v[98:101]
	v_mfma_f32_16x16x32_bf16 v[86:89], v[162:165], v[196:199], v[86:89]
	v_mfma_f32_16x16x32_bf16 v[82:85], v[170:173], v[196:199], v[82:85]
	v_mfma_f32_16x16x32_bf16 v[70:73], v[162:165], v[204:207], v[70:73]
	v_mfma_f32_16x16x32_bf16 v[66:69], v[170:173], v[204:207], v[66:69]
	s_setprio 0
	s_barrier
; #define PG8_STAGE(bufoff, gbase, voff) do { _Pragma("unroll") for (int _i = 0; _i < 2; ++_i) \
;         __builtin_amdgcn_global_load_lds((const unsigned*)((const char*)(gbase) + (voff)[_i]), (PG8_LAS unsigned*)(lds + (bufoff) + ldsw + _i * 8192), 16, 0, 0); } while (0)
; #define PG8_LDA(dst, b, h) do { _Pragma("unroll") for (int m = 0; m < 4; ++m) _Pragma("unroll") for (int k = 0; k < 2; ++k) dst[m][k] = *(const PG8_LAS bf16x8*)(lds + PG8_SA(b, h) + aoff + m * 2048 + k * 1024); } while (0)
; #define PG8_MMA(ai, bj, At, Bt) do { __builtin_amdgcn_s_setprio(1); _Pragma("unroll") for (int m = 0; m < 4; ++m) _Pragma("unroll") for (int n = 0; n < 2; ++n) _Pragma("unroll") for (int k = 0; k < 2; ++k) \
;         acc[ai][bj][m][n] = __builtin_amdgcn_mfma_f32_16x16x32_bf16(Bt[n][k], At[m][k], acc[ai][bj][m][n], 0, 0, 0); __builtin_amdgcn_s_setprio(0); } while (0)
; #define PG8_WAIT_V(n) asm volatile("s_waitcnt vmcnt(" #n ")" ::: "memory")
; #define PG8_WAIT_L(n) asm volatile("s_waitcnt lgkmcnt(" #n ")" ::: "memory")
; #define PG8_BAR __builtin_amdgcn_s_barrier()
; #define PG8_SCHED __builtin_amdgcn_sched_barrier(0)
; template <class Epi, class Sched, bool ALIGN_EPI = false, bool SP2 = false>
; __device__ __forceinline__ void gemm_phase(PG8_LAS unsigned char* lds, const Gemm g, const Sched& S, const Epi& E, int wave0) {
;     ...
;             PG8_WAIT_V(8); PG8_WAIT_L(0); PG8_BAR; PG8_MMA(0, 0, At, B0); PG8_MMA(0, 1, At, B1); PG8_BAR; PG8_SCHED;
;             PG8_LDA(At, 1, 1); PG8_STAGE(PG8_SB(1, 0), b3, voffB); PG8_STAGE(PG8_SB(1, 1), b3 + hstep, voffB); PG8_STAGE(PG8_SA(1, 0), a3, voffA);
;             PG8_WAIT_V(8); PG8_WAIT_L(0); PG8_BAR; PG8_MMA(1, 0, At, B0); PG8_MMA(1, 1, At, B1); PG8_BAR; PG8_SCHED;
	s_add_i32 s42, s86, s61
	v_lshl_add_u64 v[208:209], v[208:209], 0, s[34:35]
	s_mov_b32 m0, s42
	ds_read_b128 v[176:179], v175 offset:49152
	ds_read_b128 v[180:183], v175 offset:50176
	ds_read_b128 v[184:187], v175 offset:51200
	ds_read_b128 v[188:191], v175 offset:52224
	ds_read_b128 v[192:195], v175 offset:53248
	ds_read_b128 v[196:199], v175 offset:54272
	ds_read_b128 v[200:203], v175 offset:55296
	ds_read_b128 v[204:207], v175 offset:56320
	global_load_lds_dwordx4 v[208:209], off
	s_add_i32 m0, s42, 0x2000
	s_add_u32 s4, s4, 0x40080
	v_lshl_add_u64 v[208:209], v[210:211], 0, s[34:35]
	s_addc_u32 s5, s5, 0
	s_add_i32 s42, s87, s61
	global_load_lds_dwordx4 v[208:209], off
	v_lshl_add_u64 v[208:209], s[4:5], 0, v[150:151]
	s_mov_b32 m0, s42
	s_nop 0
	global_load_lds_dwordx4 v[208:209], off
	v_lshl_add_u64 v[208:209], s[4:5], 0, v[146:147]
	s_add_i32 m0, s42, 0x2000
	s_nop 0
	global_load_lds_dwordx4 v[208:209], off
	v_lshl_add_u64 v[208:209], v[212:213], 0, s[34:35]
	s_mov_b32 m0, s74
	s_nop 0
	global_load_lds_dwordx4 v[208:209], off
	v_lshl_add_u64 v[208:209], v[214:215], 0, s[34:35]
	s_mov_b32 m0, s75
	s_nop 0
	global_load_lds_dwordx4 v[208:209], off
	s_waitcnt vmcnt(8)
	s_waitcnt lgkmcnt(0)
	s_barrier
	s_setprio 1
	s_waitcnt lgkmcnt(0)
	v_mfma_f32_16x16x32_bf16 v[62:65], v[130:133], v[176:179], v[62:65]
	v_mfma_f32_16x16x32_bf16 v[58:61], v[138:141], v[176:179], v[58:61]
	v_mfma_f32_16x16x32_bf16 v[46:49], v[130:133], v[184:187], v[46:49]
	v_mfma_f32_16x16x32_bf16 v[42:45], v[138:141], v[184:187], v[42:45]
	v_mfma_f32_16x16x32_bf16 v[30:33], v[130:133], v[192:195], v[30:33]
	v_mfma_f32_16x16x32_bf16 v[26:29], v[138:141], v[192:195], v[26:29]
	v_mfma_f32_16x16x32_bf16 v[14:17], v[130:133], v[200:203], v[14:17]
	v_mfma_f32_16x16x32_bf16 v[10:13], v[138:141], v[200:203], v[10:13]
	v_mfma_f32_16x16x32_bf16 v[62:65], v[134:137], v[180:183], v[62:65]
	v_mfma_f32_16x16x32_bf16 v[58:61], v[142:145], v[180:183], v[58:61]
	v_mfma_f32_16x16x32_bf16 v[46:49], v[134:137], v[188:191], v[46:49]
	v_mfma_f32_16x16x32_bf16 v[42:45], v[142:145], v[188:191], v[42:45]
	v_mfma_f32_16x16x32_bf16 v[30:33], v[134:137], v[196:199], v[30:33]
	v_mfma_f32_16x16x32_bf16 v[26:29], v[142:145], v[196:199], v[26:29]
	v_mfma_f32_16x16x32_bf16 v[14:17], v[134:137], v[204:207], v[14:17]
	v_mfma_f32_16x16x32_bf16 v[10:13], v[142:145], v[204:207], v[10:13]
	s_setprio 0
	s_setprio 1
	v_mfma_f32_16x16x32_bf16 v[54:57], v[158:161], v[176:179], v[54:57]
	v_mfma_f32_16x16x32_bf16 v[50:53], v[166:169], v[176:179], v[50:53]
	v_mfma_f32_16x16x32_bf16 v[38:41], v[158:161], v[184:187], v[38:41]
	v_mfma_f32_16x16x32_bf16 v[34:37], v[166:169], v[184:187], v[34:37]
	v_mfma_f32_16x16x32_bf16 v[22:25], v[158:161], v[192:195], v[22:25]
	v_mfma_f32_16x16x32_bf16 v[18:21], v[166:169], v[192:195], v[18:21]
	v_mfma_f32_16x16x32_bf16 v[6:9], v[158:161], v[200:203], v[6:9]
	v_mfma_f32_16x16x32_bf16 v[2:5], v[166:169], v[200:203], v[2:5]
	v_mfma_f32_16x16x32_bf16 v[54:57], v[162:165], v[180:183], v[54:57]
	v_mfma_f32_16x16x32_bf16 v[50:53], v[170:173], v[180:183], v[50:53]
	v_mfma_f32_16x16x32_bf16 v[38:41], v[162:165], v[188:191], v[38:41]
	v_mfma_f32_16x16x32_bf16 v[34:37], v[170:173], v[188:191], v[34:37]
	v_mfma_f32_16x16x32_bf16 v[22:25], v[162:165], v[196:199], v[22:25]
	v_mfma_f32_16x16x32_bf16 v[18:21], v[170:173], v[196:199], v[18:21]
	v_mfma_f32_16x16x32_bf16 v[6:9], v[162:165], v[204:207], v[6:9]
	v_mfma_f32_16x16x32_bf16 v[2:5], v[170:173], v[204:207], v[2:5]
	s_setprio 0
	s_barrier
	s_add_i32 s85, s85, 2
	s_add_u32 s0, s0, 0x100
	s_addc_u32 s1, s1, 0
	s_add_u32 s83, s83, 0x100
	s_addc_u32 s84, s84, 0
	s_cmp_gt_u32 s85, 13
	s_cbranch_scc0 .LBB0_195
	s_and_b64 vcc, exec, s[48:49]
	s_cbranch_vccz .LBB0_198
	s_barrier
